# EpiResid x4: second half's residual-base loads issued right after the first half's (new registers, SGPR-base form), waits re-derived
# baseline (speedup 1.0000x reference)
.LBB0_624:
	v_add_u32_e32 v166, s47, v132
	v_or_b32_e32 v128, s14, v198
	v_mov_b32_e32 v165, 0
	v_lshlrev_b32_e32 v164, 1, v128
	v_ashrrev_i32_e32 v167, 31, v166
	v_lshl_add_u64 v[168:169], s[8:9], 0, v[164:165]
	v_lshlrev_b64 v[214:215], 11, v[166:167]
	v_lshl_add_u64 v[128:129], v[168:169], 0, v[214:215]
	global_load_dwordx4 v[206:209], v[128:129], off
	global_load_dwordx4 v[210:213], v[128:129], off offset:256
	v_or_b32_e32 v178, 16, v166
	v_or_b32_e32 v174, 32, v166
	v_or_b32_e32 v170, 48, v166
	v_ashrrev_i32_e32 v179, 31, v178
	v_ashrrev_i32_e32 v175, 31, v174
	v_ashrrev_i32_e32 v171, 31, v170
	v_lshlrev_b64 v[180:181], 11, v[178:179]
	v_lshlrev_b64 v[176:177], 11, v[174:175]
	v_lshlrev_b64 v[172:173], 11, v[170:171]
	v_lshl_add_u64 v[128:129], v[168:169], 0, v[180:181]
	v_lshl_add_u64 v[130:131], v[168:169], 0, v[176:177]
	v_lshl_add_u64 v[202:203], v[168:169], 0, v[172:173]
	global_load_dwordx4 v[148:151], v[128:129], off
	global_load_dwordx4 v[144:147], v[128:129], off offset:256
	global_load_dwordx4 v[140:143], v[130:131], off
	global_load_dwordx4 v[136:139], v[130:131], off offset:256
	global_load_dwordx4 v[132:135], v[202:203], off
	s_nop 0
	global_load_dwordx4 v[128:131], v[202:203], off offset:256
	s_add_u32 s98, s8, 0x40000
	s_addc_u32 s99, s9, 0
	v_lshl_add_u32 v224, v166, 11, v164
	global_load_dwordx4 v[232:235], v224, s[98:99]
	global_load_dwordx4 v[236:239], v224, s[98:99] offset:256
	v_add_u32_e32 v224, 0x8000, v224
	global_load_dwordx4 v[240:243], v224, s[98:99]
	global_load_dwordx4 v[244:247], v224, s[98:99] offset:256
	v_xor_b32_e32 v201, 16, v182
	v_xor_b32_e32 v202, 32, v182
	v_cmp_lt_i32_e32 vcc, v201, v183
	s_waitcnt vmcnt(4)
	v_lshlrev_b32_e32 v216, 16, v206
	v_cndmask_b32_e32 v201, v182, v201, vcc
	v_cmp_lt_i32_e32 vcc, v202, v183
	v_and_b32_e32 v217, 0xffff0000, v206
	v_lshlrev_b32_e32 v206, 16, v207
	v_and_b32_e32 v207, 0xffff0000, v207
	v_lshlrev_b32_e32 v220, 16, v210
	v_and_b32_e32 v221, 0xffff0000, v210
	v_lshlrev_b32_e32 v210, 16, v211
	v_and_b32_e32 v211, 0xffff0000, v211
	v_cndmask_b32_e32 v203, v182, v202, vcc
	v_lshlrev_b32_e32 v218, 16, v208
	v_and_b32_e32 v219, 0xffff0000, v208
	v_lshlrev_b32_e32 v208, 16, v209
	v_and_b32_e32 v209, 0xffff0000, v209
	v_lshlrev_b32_e32 v222, 16, v212
	v_and_b32_e32 v223, 0xffff0000, v212
	v_pk_add_f32 v[126:127], v[126:127], v[206:207]
	v_pk_add_f32 v[124:125], v[124:125], v[216:217]
	v_pk_add_f32 v[118:119], v[118:119], v[210:211]
	v_pk_add_f32 v[116:117], v[116:117], v[220:221]
	v_lshlrev_b32_e32 v202, 2, v201
	v_lshlrev_b32_e32 v201, 2, v203
	v_lshlrev_b32_e32 v212, 16, v213
	v_and_b32_e32 v213, 0xffff0000, v213
	v_pk_add_f32 v[122:123], v[122:123], v[208:209]
	v_pk_add_f32 v[120:121], v[120:121], v[218:219]
	v_pk_add_f32 v[208:209], v[112:113], v[222:223]
	v_cvt_pk_bf16_f32 v112, v124, v125
	v_cvt_pk_bf16_f32 v113, v126, v127
	v_mul_f32_e32 v125, v125, v125
	v_mul_f32_e32 v127, v127, v127
	v_mul_f32_e32 v203, v117, v117
	v_mul_f32_e32 v204, v119, v119
	v_pk_add_f32 v[206:207], v[114:115], v[212:213]
	v_cvt_pk_bf16_f32 v114, v120, v121
	v_cvt_pk_bf16_f32 v115, v122, v123
	v_mul_f32_e32 v121, v121, v121
	v_mul_f32_e32 v123, v123, v123
	v_mul_f32_e32 v210, v209, v209
	v_fmac_f32_e32 v125, v124, v124
	v_fmac_f32_e32 v127, v126, v126
	v_fmac_f32_e32 v203, v116, v116
	v_fmac_f32_e32 v204, v118, v118
	v_mul_f32_e32 v211, v207, v207
	v_fmac_f32_e32 v121, v120, v120
	v_fmac_f32_e32 v123, v122, v122
	v_fmac_f32_e32 v210, v208, v208
	v_add_f32_e32 v120, v125, v127
	v_add_f32_e32 v122, v203, v204
	v_fmac_f32_e32 v211, v206, v206
	v_add_f32_e32 v120, v121, v120
	v_add_f32_e32 v121, v210, v122
	v_add_f32_e32 v120, v123, v120
	v_add_f32_e32 v121, v211, v121
	v_add_f32_e32 v122, v120, v121
	ds_bpermute_b32 v123, v202, v122
	v_lshl_add_u64 v[120:121], s[26:27], 0, v[214:215]
	v_lshl_add_u64 v[120:121], v[120:121], 0, v[164:165]
	global_store_dwordx4 v[120:121], v[112:115], off
	s_waitcnt lgkmcnt(0)
	s_nop 0
	v_add_f32_e32 v112, v122, v123
	ds_bpermute_b32 v113, v201, v112
	v_cvt_pk_bf16_f32 v114, v116, v117
	v_cvt_pk_bf16_f32 v115, v118, v119
	v_cvt_pk_bf16_f32 v116, v208, v209
	v_cvt_pk_bf16_f32 v117, v206, v207
	global_store_dwordx4 v[120:121], v[114:117], off offset:256
	s_and_saveexec_b64 s[0:1], s[4:5]
	s_cbranch_execz .LBB0_626
	v_lshl_add_u64 v[114:115], v[166:167], 2, s[12:13]
	s_waitcnt lgkmcnt(0)
	v_add_f32_e32 v112, v112, v113
	global_atomic_add_f32 v[114:115], v112, off

.LBB0_632:
	s_or_b64 exec, exec, s[0:1]
	v_add_u32_e32 v100, 0x80, v166
	v_ashrrev_i32_e32 v101, 31, v100
	v_lshlrev_b64 v[110:111], 11, v[100:101]
	s_waitcnt lgkmcnt(0)
	v_lshl_add_u64 v[64:65], v[168:169], 0, v[110:111]
	v_add_u32_e32 v96, 0x90, v166
	v_add_u32_e32 v92, 0xa0, v166
	v_add_u32_e32 v88, 0xb0, v166
	v_ashrrev_i32_e32 v97, 31, v96
	v_ashrrev_i32_e32 v93, 31, v92
	v_ashrrev_i32_e32 v89, 31, v88
	v_lshlrev_b64 v[98:99], 11, v[96:97]
	v_lshlrev_b64 v[94:95], 11, v[92:93]
	v_lshlrev_b64 v[90:91], 11, v[88:89]
	v_lshl_add_u64 v[64:65], v[168:169], 0, v[98:99]
	v_lshl_add_u64 v[66:67], v[168:169], 0, v[94:95]
	v_lshl_add_u64 v[112:113], v[168:169], 0, v[90:91]
	global_load_dwordx4 v[76:79], v[66:67], off
	global_load_dwordx4 v[72:75], v[66:67], off offset:256
	global_load_dwordx4 v[68:71], v[112:113], off
	s_nop 0
	global_load_dwordx4 v[64:67], v[112:113], off offset:256
	v_lshl_add_u64 v[110:111], s[26:27], 0, v[110:111]
	v_mov_b32_e32 v165, 0
	s_waitcnt vmcnt(12)
	v_lshlrev_b32_e32 v112, 16, v232
	v_and_b32_e32 v113, 0xffff0000, v232
	v_lshlrev_b32_e32 v102, 16, v233
	v_and_b32_e32 v103, 0xffff0000, v233
	s_waitcnt vmcnt(12)
	v_lshlrev_b32_e32 v116, 16, v236
	v_and_b32_e32 v117, 0xffff0000, v236
	v_lshlrev_b32_e32 v106, 16, v237
	v_and_b32_e32 v107, 0xffff0000, v237
	v_lshlrev_b32_e32 v114, 16, v234
	v_and_b32_e32 v115, 0xffff0000, v234
	v_lshlrev_b32_e32 v104, 16, v235
	v_and_b32_e32 v105, 0xffff0000, v235
	v_lshlrev_b32_e32 v118, 16, v238
	v_and_b32_e32 v119, 0xffff0000, v238
	v_pk_add_f32 v[62:63], v[62:63], v[102:103]
	v_pk_add_f32 v[60:61], v[60:61], v[112:113]
	v_pk_add_f32 v[54:55], v[54:55], v[106:107]
	v_pk_add_f32 v[52:53], v[52:53], v[116:117]
	v_lshlrev_b32_e32 v108, 16, v239
	v_and_b32_e32 v109, 0xffff0000, v239
	v_pk_add_f32 v[58:59], v[58:59], v[104:105]
	v_pk_add_f32 v[56:57], v[56:57], v[114:115]
	v_pk_add_f32 v[104:105], v[48:49], v[118:119]
	v_cvt_pk_bf16_f32 v48, v60, v61
	v_cvt_pk_bf16_f32 v49, v62, v63
	v_mul_f32_e32 v61, v61, v61
	v_mul_f32_e32 v63, v63, v63
	v_mul_f32_e32 v106, v53, v53
	v_mul_f32_e32 v107, v55, v55
	v_pk_add_f32 v[102:103], v[50:51], v[108:109]
	v_cvt_pk_bf16_f32 v50, v56, v57
	v_cvt_pk_bf16_f32 v51, v58, v59
	v_mul_f32_e32 v57, v57, v57
	v_mul_f32_e32 v59, v59, v59
	v_mul_f32_e32 v108, v105, v105
	v_fmac_f32_e32 v61, v60, v60
	v_fmac_f32_e32 v63, v62, v62
	v_fmac_f32_e32 v106, v52, v52
	v_fmac_f32_e32 v107, v54, v54
	v_mul_f32_e32 v109, v103, v103
	v_fmac_f32_e32 v57, v56, v56
	v_fmac_f32_e32 v59, v58, v58
	v_fmac_f32_e32 v108, v104, v104
	v_add_f32_e32 v56, v61, v63
	v_add_f32_e32 v58, v106, v107
	v_fmac_f32_e32 v109, v102, v102
	v_add_f32_e32 v56, v57, v56
	v_add_f32_e32 v57, v108, v58
	v_add_f32_e32 v56, v59, v56
	v_add_f32_e32 v57, v109, v57
	v_add_f32_e32 v58, v56, v57
	ds_bpermute_b32 v59, v202, v58
	v_lshl_add_u64 v[56:57], v[110:111], 0, v[164:165]
	global_store_dwordx4 v[56:57], v[48:51], off
	s_waitcnt lgkmcnt(0)
	s_nop 0
	v_add_f32_e32 v48, v58, v59
	ds_bpermute_b32 v49, v201, v48
	v_cvt_pk_bf16_f32 v50, v52, v53
	v_cvt_pk_bf16_f32 v51, v54, v55
	v_cvt_pk_bf16_f32 v52, v104, v105
	v_cvt_pk_bf16_f32 v53, v102, v103
	global_store_dwordx4 v[56:57], v[50:53], off offset:256
	s_and_saveexec_b64 s[0:1], s[4:5]
	s_cbranch_execz .LBB0_634
	v_lshl_add_u64 v[50:51], v[100:101], 2, s[12:13]
	s_waitcnt lgkmcnt(0)
	v_add_f32_e32 v48, v48, v49
	global_atomic_add_f32 v[50:51], v48, off
.LBB0_634:
	s_or_b64 exec, exec, s[0:1]
	v_lshlrev_b32_e32 v48, 16, v240
	s_waitcnt lgkmcnt(0)
	v_and_b32_e32 v49, 0xffff0000, v240
	v_lshlrev_b32_e32 v50, 16, v241
	v_and_b32_e32 v51, 0xffff0000, v241
	v_lshlrev_b32_e32 v52, 16, v242
	v_and_b32_e32 v53, 0xffff0000, v242
	v_pk_add_f32 v[44:45], v[44:45], v[48:49]
	v_pk_add_f32 v[46:47], v[46:47], v[50:51]
	v_pk_add_f32 v[50:51], v[40:41], v[52:53]
	v_cvt_pk_bf16_f32 v40, v44, v45
	v_mul_f32_e32 v45, v45, v45
	v_fmac_f32_e32 v45, v44, v44
	v_mul_f32_e32 v44, v47, v47
	v_lshlrev_b32_e32 v56, 16, v244
	v_and_b32_e32 v57, 0xffff0000, v244
	v_lshlrev_b32_e32 v58, 16, v245
	v_and_b32_e32 v59, 0xffff0000, v245
	v_fmac_f32_e32 v44, v46, v46
	v_lshlrev_b32_e32 v54, 16, v243
	v_and_b32_e32 v55, 0xffff0000, v243
	v_lshlrev_b32_e32 v60, 16, v246
	v_and_b32_e32 v61, 0xffff0000, v246
	v_add_f32_e32 v44, v45, v44
	v_mul_f32_e32 v45, v51, v51
	v_pk_add_f32 v[38:39], v[38:39], v[58:59]
	v_pk_add_f32 v[36:37], v[36:37], v[56:57]
	v_pk_add_f32 v[48:49], v[42:43], v[54:55]
	v_cvt_pk_bf16_f32 v41, v46, v47
	v_fmac_f32_e32 v45, v50, v50
	v_pk_add_f32 v[46:47], v[32:33], v[60:61]
	v_mul_f32_e32 v32, v37, v37
	v_mul_f32_e32 v33, v39, v39
	v_add_f32_e32 v44, v45, v44
	v_mul_f32_e32 v45, v49, v49
	v_fmac_f32_e32 v32, v36, v36
	v_fmac_f32_e32 v33, v38, v38
	v_lshlrev_b32_e32 v62, 16, v247
	v_and_b32_e32 v63, 0xffff0000, v247
	v_fmac_f32_e32 v45, v48, v48
	v_add_f32_e32 v32, v32, v33
	v_mul_f32_e32 v33, v47, v47
	v_cvt_pk_bf16_f32 v43, v48, v49
	v_add_f32_e32 v48, v45, v44
	v_pk_add_f32 v[44:45], v[34:35], v[62:63]
	v_fmac_f32_e32 v33, v46, v46
	v_add_f32_e32 v32, v33, v32
	v_mul_f32_e32 v33, v45, v45
	v_fmac_f32_e32 v33, v44, v44
	v_add_f32_e32 v32, v33, v32
	v_add_f32_e32 v35, v48, v32
	v_cvt_pk_bf16_f32 v42, v50, v51
	ds_bpermute_b32 v50, v202, v35
	v_lshl_add_u64 v[32:33], s[26:27], 0, v[98:99]
	v_lshl_add_u64 v[48:49], v[32:33], 0, v[164:165]
	v_cvt_pk_bf16_f32 v34, v36, v37
	v_cvt_pk_bf16_f32 v36, v46, v47
	s_waitcnt lgkmcnt(0)
	v_add_f32_e32 v32, v35, v50
	ds_bpermute_b32 v33, v201, v32
	v_cvt_pk_bf16_f32 v35, v38, v39
	v_cvt_pk_bf16_f32 v37, v44, v45
	global_store_dwordx4 v[48:49], v[40:43], off
	global_store_dwordx4 v[48:49], v[34:37], off offset:256
	s_and_saveexec_b64 s[0:1], s[4:5]
	s_cbranch_execz .LBB0_636
	v_lshl_add_u64 v[34:35], v[96:97], 2, s[12:13]
	s_waitcnt lgkmcnt(0)
	v_add_f32_e32 v32, v32, v33
	global_atomic_add_f32 v[34:35], v32, off

.LBB0_687:
	s_andn2_b64 vcc, exec, s[10:11]
	s_cbranch_vccnz .LBB0_705
	v_add_u32_e32 v154, s47, v140
	v_or_b32_e32 v128, s23, v198
	v_mov_b32_e32 v153, 0
	v_lshlrev_b32_e32 v152, 1, v128
	v_ashrrev_i32_e32 v155, 31, v154
	v_lshl_add_u64 v[156:157], s[26:27], 0, v[152:153]
	v_lshlrev_b64 v[180:181], 11, v[154:155]
	v_lshl_add_u64 v[128:129], v[156:157], 0, v[180:181]
	global_load_dwordx4 v[172:175], v[128:129], off
	global_load_dwordx4 v[176:179], v[128:129], off offset:256
	v_or_b32_e32 v166, 16, v154
	v_or_b32_e32 v162, 32, v154
	v_or_b32_e32 v158, 48, v154
	v_ashrrev_i32_e32 v167, 31, v166
	v_ashrrev_i32_e32 v163, 31, v162
	v_ashrrev_i32_e32 v159, 31, v158
	v_lshlrev_b64 v[168:169], 11, v[166:167]
	v_lshlrev_b64 v[164:165], 11, v[162:163]
	v_lshlrev_b64 v[160:161], 11, v[158:159]
	v_lshl_add_u64 v[128:129], v[156:157], 0, v[168:169]
	v_lshl_add_u64 v[130:131], v[156:157], 0, v[164:165]
	v_lshl_add_u64 v[170:171], v[156:157], 0, v[160:161]
	global_load_dwordx4 v[148:151], v[128:129], off
	global_load_dwordx4 v[144:147], v[128:129], off offset:256
	global_load_dwordx4 v[140:143], v[130:131], off
	global_load_dwordx4 v[136:139], v[130:131], off offset:256
	global_load_dwordx4 v[132:135], v[170:171], off
	s_nop 0
	global_load_dwordx4 v[128:131], v[170:171], off offset:256
	s_add_u32 s98, s26, 0x40000
	s_addc_u32 s99, s27, 0
	v_lshl_add_u32 v224, v154, 11, v152
	global_load_dwordx4 v[208:211], v224, s[98:99]
	global_load_dwordx4 v[212:215], v224, s[98:99] offset:256
	v_add_u32_e32 v224, 0x8000, v224
	global_load_dwordx4 v[216:219], v224, s[98:99]
	global_load_dwordx4 v[220:223], v224, s[98:99] offset:256
	v_add_u32_e32 v224, 0x8000, v224
	global_load_dwordx4 v[232:235], v224, s[98:99]
	global_load_dwordx4 v[236:239], v224, s[98:99] offset:256
	v_add_u32_e32 v224, 0x8000, v224
	global_load_dwordx4 v[240:243], v224, s[98:99]
	global_load_dwordx4 v[244:247], v224, s[98:99] offset:256
	v_xor_b32_e32 v170, 16, v182
	v_xor_b32_e32 v171, 32, v182
	v_cmp_lt_i32_e32 vcc, v170, v183
	s_add_u32 s0, s96, 0x20000
	s_addc_u32 s1, s97, 0
	v_cndmask_b32_e32 v170, v182, v170, vcc
	v_cmp_lt_i32_e32 vcc, v171, v183
	s_waitcnt vmcnt(8)
	v_and_b32_e32 v183, 0xffff0000, v172
	v_cndmask_b32_e32 v182, v182, v171, vcc
	v_lshlrev_b32_e32 v171, 2, v170
	v_lshlrev_b32_e32 v170, 2, v182
	v_lshlrev_b32_e32 v182, 16, v172
	v_lshlrev_b32_e32 v172, 16, v173
	v_and_b32_e32 v173, 0xffff0000, v173
	v_lshlrev_b32_e32 v186, 16, v176
	v_and_b32_e32 v187, 0xffff0000, v176
	v_lshlrev_b32_e32 v176, 16, v177
	v_and_b32_e32 v177, 0xffff0000, v177
	v_lshlrev_b32_e32 v184, 16, v174
	v_and_b32_e32 v185, 0xffff0000, v174
	v_lshlrev_b32_e32 v174, 16, v175
	v_and_b32_e32 v175, 0xffff0000, v175
	v_lshlrev_b32_e32 v188, 16, v178
	v_and_b32_e32 v189, 0xffff0000, v178
	v_pk_add_f32 v[126:127], v[126:127], v[172:173]
	v_pk_add_f32 v[124:125], v[124:125], v[182:183]
	v_pk_add_f32 v[118:119], v[118:119], v[176:177]
	v_pk_add_f32 v[116:117], v[116:117], v[186:187]
	v_lshlrev_b32_e32 v178, 16, v179
	v_and_b32_e32 v179, 0xffff0000, v179
	v_pk_add_f32 v[122:123], v[122:123], v[174:175]
	v_pk_add_f32 v[120:121], v[120:121], v[184:185]
	v_pk_add_f32 v[174:175], v[112:113], v[188:189]
	v_cvt_pk_bf16_f32 v112, v124, v125
	v_cvt_pk_bf16_f32 v113, v126, v127
	v_mul_f32_e32 v125, v125, v125
	v_mul_f32_e32 v127, v127, v127
	v_mul_f32_e32 v176, v117, v117
	v_mul_f32_e32 v177, v119, v119
	v_pk_add_f32 v[172:173], v[114:115], v[178:179]
	v_cvt_pk_bf16_f32 v114, v120, v121
	v_cvt_pk_bf16_f32 v115, v122, v123
	v_mul_f32_e32 v121, v121, v121
	v_mul_f32_e32 v123, v123, v123
	v_mul_f32_e32 v178, v175, v175
	v_fmac_f32_e32 v125, v124, v124
	v_fmac_f32_e32 v127, v126, v126
	v_fmac_f32_e32 v176, v116, v116
	v_fmac_f32_e32 v177, v118, v118
	v_mul_f32_e32 v179, v173, v173
	v_fmac_f32_e32 v121, v120, v120
	v_fmac_f32_e32 v123, v122, v122
	v_fmac_f32_e32 v178, v174, v174
	v_add_f32_e32 v120, v125, v127
	v_add_f32_e32 v122, v176, v177
	v_fmac_f32_e32 v179, v172, v172
	v_add_f32_e32 v120, v121, v120
	v_add_f32_e32 v121, v178, v122
	v_add_f32_e32 v120, v123, v120
	v_add_f32_e32 v121, v179, v121
	v_add_f32_e32 v122, v120, v121
	ds_bpermute_b32 v123, v171, v122
	v_lshl_add_u64 v[120:121], s[8:9], 0, v[180:181]
	v_lshl_add_u64 v[120:121], v[120:121], 0, v[152:153]
	global_store_dwordx4 v[120:121], v[112:115], off
	s_waitcnt lgkmcnt(0)
	s_nop 0
	v_add_f32_e32 v112, v122, v123
	ds_bpermute_b32 v113, v170, v112
	v_cvt_pk_bf16_f32 v114, v116, v117
	v_cvt_pk_bf16_f32 v115, v118, v119
	v_cvt_pk_bf16_f32 v116, v174, v175
	v_cvt_pk_bf16_f32 v117, v172, v173
	global_store_dwordx4 v[120:121], v[114:117], off offset:256
	s_and_saveexec_b64 s[2:3], s[4:5]
	s_cbranch_execz .LBB0_690
	v_lshl_add_u64 v[114:115], v[154:155], 2, s[0:1]
	s_waitcnt lgkmcnt(0)
	v_add_f32_e32 v112, v112, v113
	global_atomic_add_f32 v[114:115], v112, off

.LBB0_696:
	s_or_b64 exec, exec, s[2:3]
	v_add_u32_e32 v100, 0x80, v154
	v_ashrrev_i32_e32 v101, 31, v100
	v_lshlrev_b64 v[110:111], 11, v[100:101]
	s_waitcnt lgkmcnt(0)
	v_lshl_add_u64 v[64:65], v[156:157], 0, v[110:111]
	v_add_u32_e32 v96, 0x90, v154
	v_add_u32_e32 v92, 0xa0, v154
	v_add_u32_e32 v88, 0xb0, v154
	v_ashrrev_i32_e32 v97, 31, v96
	v_ashrrev_i32_e32 v93, 31, v92
	v_ashrrev_i32_e32 v89, 31, v88
	v_lshlrev_b64 v[98:99], 11, v[96:97]
	v_lshlrev_b64 v[94:95], 11, v[92:93]
	v_lshlrev_b64 v[90:91], 11, v[88:89]
	v_lshl_add_u64 v[112:113], v[156:157], 0, v[98:99]
	v_lshl_add_u64 v[114:115], v[156:157], 0, v[94:95]
	v_lshl_add_u64 v[116:117], v[156:157], 0, v[90:91]
	v_lshl_add_u64 v[110:111], s[8:9], 0, v[110:111]
	v_mov_b32_e32 v153, 0
	s_waitcnt vmcnt(8)
	v_lshlrev_b32_e32 v112, 16, v208
	v_and_b32_e32 v113, 0xffff0000, v208
	v_lshlrev_b32_e32 v102, 16, v209
	v_and_b32_e32 v103, 0xffff0000, v209
	v_lshlrev_b32_e32 v116, 16, v212
	v_and_b32_e32 v117, 0xffff0000, v212
	v_lshlrev_b32_e32 v106, 16, v213
	v_and_b32_e32 v107, 0xffff0000, v213
	v_lshlrev_b32_e32 v114, 16, v210
	v_and_b32_e32 v115, 0xffff0000, v210
	v_lshlrev_b32_e32 v104, 16, v211
	v_and_b32_e32 v105, 0xffff0000, v211
	v_lshlrev_b32_e32 v118, 16, v214
	v_and_b32_e32 v119, 0xffff0000, v214
	v_pk_add_f32 v[62:63], v[62:63], v[102:103]
	v_pk_add_f32 v[60:61], v[60:61], v[112:113]
	v_pk_add_f32 v[54:55], v[54:55], v[106:107]
	v_pk_add_f32 v[52:53], v[52:53], v[116:117]
	v_lshlrev_b32_e32 v108, 16, v215
	v_and_b32_e32 v109, 0xffff0000, v215
	v_pk_add_f32 v[58:59], v[58:59], v[104:105]
	v_pk_add_f32 v[56:57], v[56:57], v[114:115]
	v_pk_add_f32 v[104:105], v[48:49], v[118:119]
	v_cvt_pk_bf16_f32 v48, v60, v61
	v_cvt_pk_bf16_f32 v49, v62, v63
	v_mul_f32_e32 v61, v61, v61
	v_mul_f32_e32 v63, v63, v63
	v_mul_f32_e32 v106, v53, v53
	v_mul_f32_e32 v107, v55, v55
	v_pk_add_f32 v[102:103], v[50:51], v[108:109]
	v_cvt_pk_bf16_f32 v50, v56, v57
	v_cvt_pk_bf16_f32 v51, v58, v59
	v_mul_f32_e32 v57, v57, v57
	v_mul_f32_e32 v59, v59, v59
	v_mul_f32_e32 v108, v105, v105
	v_fmac_f32_e32 v61, v60, v60
	v_fmac_f32_e32 v63, v62, v62
	v_fmac_f32_e32 v106, v52, v52
	v_fmac_f32_e32 v107, v54, v54
	v_mul_f32_e32 v109, v103, v103
	v_fmac_f32_e32 v57, v56, v56
	v_fmac_f32_e32 v59, v58, v58
	v_fmac_f32_e32 v108, v104, v104
	v_add_f32_e32 v56, v61, v63
	v_add_f32_e32 v58, v106, v107
	v_fmac_f32_e32 v109, v102, v102
	v_add_f32_e32 v56, v57, v56
	v_add_f32_e32 v57, v108, v58
	v_add_f32_e32 v56, v59, v56
	v_add_f32_e32 v57, v109, v57
	v_add_f32_e32 v58, v56, v57
	ds_bpermute_b32 v59, v171, v58
	v_lshl_add_u64 v[56:57], v[110:111], 0, v[152:153]
	global_store_dwordx4 v[56:57], v[48:51], off
	s_waitcnt lgkmcnt(0)
	s_nop 0
	v_add_f32_e32 v48, v58, v59
	ds_bpermute_b32 v49, v170, v48
	v_cvt_pk_bf16_f32 v50, v52, v53
	v_cvt_pk_bf16_f32 v51, v54, v55
	v_cvt_pk_bf16_f32 v52, v104, v105
	v_cvt_pk_bf16_f32 v53, v102, v103
	global_store_dwordx4 v[56:57], v[50:53], off offset:256
	s_and_saveexec_b64 s[2:3], s[4:5]
	s_cbranch_execz .LBB0_698
	v_lshl_add_u64 v[50:51], v[100:101], 2, s[0:1]
	s_waitcnt lgkmcnt(0)
	v_add_f32_e32 v48, v48, v49
	global_atomic_add_f32 v[50:51], v48, off
.LBB0_698:
	s_or_b64 exec, exec, s[2:3]
	v_lshlrev_b32_e32 v48, 16, v216
	s_waitcnt lgkmcnt(0)
	v_and_b32_e32 v49, 0xffff0000, v216
	v_lshlrev_b32_e32 v50, 16, v217
	v_and_b32_e32 v51, 0xffff0000, v217
	v_lshlrev_b32_e32 v52, 16, v218
	v_and_b32_e32 v53, 0xffff0000, v218
	v_pk_add_f32 v[44:45], v[44:45], v[48:49]
	v_pk_add_f32 v[46:47], v[46:47], v[50:51]
	v_pk_add_f32 v[50:51], v[40:41], v[52:53]
	v_cvt_pk_bf16_f32 v40, v44, v45
	v_mul_f32_e32 v45, v45, v45
	v_fmac_f32_e32 v45, v44, v44
	v_mul_f32_e32 v44, v47, v47
	v_lshlrev_b32_e32 v56, 16, v220
	v_and_b32_e32 v57, 0xffff0000, v220
	v_lshlrev_b32_e32 v58, 16, v221
	v_and_b32_e32 v59, 0xffff0000, v221
	v_fmac_f32_e32 v44, v46, v46
	v_lshlrev_b32_e32 v54, 16, v219
	v_and_b32_e32 v55, 0xffff0000, v219
	v_lshlrev_b32_e32 v60, 16, v222
	v_and_b32_e32 v61, 0xffff0000, v222
	v_add_f32_e32 v44, v45, v44
	v_mul_f32_e32 v45, v51, v51
	v_pk_add_f32 v[38:39], v[38:39], v[58:59]
	v_pk_add_f32 v[36:37], v[36:37], v[56:57]
	v_pk_add_f32 v[48:49], v[42:43], v[54:55]
	v_cvt_pk_bf16_f32 v41, v46, v47
	v_fmac_f32_e32 v45, v50, v50
	v_pk_add_f32 v[46:47], v[32:33], v[60:61]
	v_mul_f32_e32 v32, v37, v37
	v_mul_f32_e32 v33, v39, v39
	v_add_f32_e32 v44, v45, v44
	v_mul_f32_e32 v45, v49, v49
	v_fmac_f32_e32 v32, v36, v36
	v_fmac_f32_e32 v33, v38, v38
	v_lshlrev_b32_e32 v62, 16, v223
	v_and_b32_e32 v63, 0xffff0000, v223
	v_fmac_f32_e32 v45, v48, v48
	v_add_f32_e32 v32, v32, v33
	v_mul_f32_e32 v33, v47, v47
	v_cvt_pk_bf16_f32 v43, v48, v49
	v_add_f32_e32 v48, v45, v44
	v_pk_add_f32 v[44:45], v[34:35], v[62:63]
	v_fmac_f32_e32 v33, v46, v46
	v_add_f32_e32 v32, v33, v32
	v_mul_f32_e32 v33, v45, v45
	v_fmac_f32_e32 v33, v44, v44
	v_add_f32_e32 v32, v33, v32
	v_add_f32_e32 v35, v48, v32
	v_cvt_pk_bf16_f32 v42, v50, v51
	ds_bpermute_b32 v50, v171, v35
	v_lshl_add_u64 v[32:33], s[8:9], 0, v[98:99]
	v_lshl_add_u64 v[48:49], v[32:33], 0, v[152:153]
	v_cvt_pk_bf16_f32 v34, v36, v37
	v_cvt_pk_bf16_f32 v36, v46, v47
	s_waitcnt lgkmcnt(0)
	v_add_f32_e32 v32, v35, v50
	ds_bpermute_b32 v33, v170, v32
	v_cvt_pk_bf16_f32 v35, v38, v39
	v_cvt_pk_bf16_f32 v37, v44, v45
	global_store_dwordx4 v[48:49], v[40:43], off
	global_store_dwordx4 v[48:49], v[34:37], off offset:256
	s_and_saveexec_b64 s[2:3], s[4:5]
	s_cbranch_execz .LBB0_700
	v_lshl_add_u64 v[34:35], v[96:97], 2, s[0:1]
	s_waitcnt lgkmcnt(0)
	v_add_f32_e32 v32, v32, v33
	global_atomic_add_f32 v[34:35], v32, off
.LBB0_700:
	s_or_b64 exec, exec, s[2:3]
	v_lshlrev_b32_e32 v32, 16, v232
	s_waitcnt lgkmcnt(0)
	v_and_b32_e32 v33, 0xffff0000, v232
	v_lshlrev_b32_e32 v34, 16, v233
	v_and_b32_e32 v35, 0xffff0000, v233
	v_lshlrev_b32_e32 v36, 16, v234
	v_and_b32_e32 v37, 0xffff0000, v234
	v_pk_add_f32 v[28:29], v[28:29], v[32:33]
	v_pk_add_f32 v[30:31], v[30:31], v[34:35]
	v_pk_add_f32 v[34:35], v[24:25], v[36:37]
	v_cvt_pk_bf16_f32 v24, v28, v29
	v_mul_f32_e32 v29, v29, v29
	v_fmac_f32_e32 v29, v28, v28
	v_mul_f32_e32 v28, v31, v31
	v_lshlrev_b32_e32 v40, 16, v236
	v_and_b32_e32 v41, 0xffff0000, v236
	v_lshlrev_b32_e32 v42, 16, v237
	v_and_b32_e32 v43, 0xffff0000, v237
	v_fmac_f32_e32 v28, v30, v30
	v_lshlrev_b32_e32 v38, 16, v235
	v_and_b32_e32 v39, 0xffff0000, v235
	v_lshlrev_b32_e32 v44, 16, v238
	v_and_b32_e32 v45, 0xffff0000, v238
	v_add_f32_e32 v28, v29, v28
	v_mul_f32_e32 v29, v35, v35
	v_pk_add_f32 v[22:23], v[22:23], v[42:43]
	v_pk_add_f32 v[20:21], v[20:21], v[40:41]
	v_pk_add_f32 v[32:33], v[26:27], v[38:39]
	v_cvt_pk_bf16_f32 v25, v30, v31
	v_fmac_f32_e32 v29, v34, v34
	v_pk_add_f32 v[30:31], v[16:17], v[44:45]
	v_mul_f32_e32 v16, v21, v21
	v_mul_f32_e32 v17, v23, v23
	v_add_f32_e32 v28, v29, v28
	v_mul_f32_e32 v29, v33, v33
	v_fmac_f32_e32 v16, v20, v20
	v_fmac_f32_e32 v17, v22, v22
	v_lshlrev_b32_e32 v46, 16, v239
	v_and_b32_e32 v47, 0xffff0000, v239
	v_fmac_f32_e32 v29, v32, v32
	v_add_f32_e32 v16, v16, v17
	v_mul_f32_e32 v17, v31, v31
	v_cvt_pk_bf16_f32 v27, v32, v33
	v_add_f32_e32 v32, v29, v28
	v_pk_add_f32 v[28:29], v[18:19], v[46:47]
	v_fmac_f32_e32 v17, v30, v30
	v_add_f32_e32 v16, v17, v16
	v_mul_f32_e32 v17, v29, v29
	v_fmac_f32_e32 v17, v28, v28
	v_add_f32_e32 v16, v17, v16
	v_add_f32_e32 v16, v32, v16
	ds_bpermute_b32 v17, v171, v16
	v_lshl_add_u64 v[36:37], s[8:9], 0, v[94:95]
	v_mov_b32_e32 v153, 0
	v_cvt_pk_bf16_f32 v26, v34, v35
	v_lshl_add_u64 v[32:33], v[36:37], 0, v[152:153]
	s_waitcnt lgkmcnt(0)
	v_add_f32_e32 v16, v16, v17
	ds_bpermute_b32 v17, v170, v16
	v_cvt_pk_bf16_f32 v18, v20, v21
	v_cvt_pk_bf16_f32 v19, v22, v23
	v_cvt_pk_bf16_f32 v20, v30, v31
	v_cvt_pk_bf16_f32 v21, v28, v29
	global_store_dwordx4 v[32:33], v[24:27], off
	global_store_dwordx4 v[32:33], v[18:21], off offset:256
	s_and_saveexec_b64 s[2:3], s[4:5]
	s_cbranch_execz .LBB0_702
	v_lshl_add_u64 v[18:19], v[92:93], 2, s[0:1]
	s_waitcnt lgkmcnt(0)
	v_add_f32_e32 v16, v16, v17
	global_atomic_add_f32 v[18:19], v16, off
.LBB0_702:
	s_or_b64 exec, exec, s[2:3]
	v_lshlrev_b32_e32 v16, 16, v240
	s_waitcnt lgkmcnt(0)
	v_and_b32_e32 v17, 0xffff0000, v240
	v_lshlrev_b32_e32 v18, 16, v241
	v_and_b32_e32 v19, 0xffff0000, v241
	v_lshlrev_b32_e32 v20, 16, v242
	v_and_b32_e32 v21, 0xffff0000, v242
	v_pk_add_f32 v[12:13], v[12:13], v[16:17]
	v_pk_add_f32 v[14:15], v[14:15], v[18:19]
	v_pk_add_f32 v[18:19], v[8:9], v[20:21]
	v_cvt_pk_bf16_f32 v8, v12, v13
	v_mul_f32_e32 v13, v13, v13
	v_fmac_f32_e32 v13, v12, v12
	v_mul_f32_e32 v12, v15, v15
	v_lshlrev_b32_e32 v24, 16, v244
	v_and_b32_e32 v25, 0xffff0000, v244
	v_lshlrev_b32_e32 v26, 16, v245
	v_and_b32_e32 v27, 0xffff0000, v245
	v_fmac_f32_e32 v12, v14, v14
	v_lshlrev_b32_e32 v22, 16, v243
	v_and_b32_e32 v23, 0xffff0000, v243
	v_lshlrev_b32_e32 v28, 16, v246
	v_and_b32_e32 v29, 0xffff0000, v246
	v_add_f32_e32 v12, v13, v12
	v_mul_f32_e32 v13, v19, v19
	v_pk_add_f32 v[6:7], v[6:7], v[26:27]
	v_pk_add_f32 v[4:5], v[4:5], v[24:25]
	v_pk_add_f32 v[16:17], v[10:11], v[22:23]
	v_cvt_pk_bf16_f32 v9, v14, v15
	v_fmac_f32_e32 v13, v18, v18
	v_pk_add_f32 v[14:15], v[0:1], v[28:29]
	v_mul_f32_e32 v0, v5, v5
	v_mul_f32_e32 v1, v7, v7
	v_add_f32_e32 v12, v13, v12
	v_mul_f32_e32 v13, v17, v17
	v_fmac_f32_e32 v0, v4, v4
	v_fmac_f32_e32 v1, v6, v6
	v_lshlrev_b32_e32 v30, 16, v247
	v_and_b32_e32 v31, 0xffff0000, v247
	v_fmac_f32_e32 v13, v16, v16
	v_add_f32_e32 v0, v0, v1
	v_mul_f32_e32 v1, v15, v15
	v_cvt_pk_bf16_f32 v11, v16, v17
	v_add_f32_e32 v16, v13, v12
	v_pk_add_f32 v[12:13], v[2:3], v[30:31]
	v_fmac_f32_e32 v1, v14, v14
	v_add_f32_e32 v0, v1, v0
	v_mul_f32_e32 v1, v13, v13
	v_fmac_f32_e32 v1, v12, v12
	v_add_f32_e32 v0, v1, v0
	v_add_f32_e32 v3, v16, v0
	v_cvt_pk_bf16_f32 v10, v18, v19
	ds_bpermute_b32 v18, v171, v3
	v_lshl_add_u64 v[0:1], s[8:9], 0, v[90:91]
	v_lshl_add_u64 v[16:17], v[0:1], 0, v[152:153]
	v_cvt_pk_bf16_f32 v2, v4, v5
	v_cvt_pk_bf16_f32 v4, v14, v15
	s_waitcnt lgkmcnt(0)
	v_add_f32_e32 v0, v3, v18
	ds_bpermute_b32 v1, v170, v0
	v_cvt_pk_bf16_f32 v3, v6, v7
	v_cvt_pk_bf16_f32 v5, v12, v13
	global_store_dwordx4 v[16:17], v[8:11], off
	global_store_dwordx4 v[16:17], v[2:5], off offset:256
	s_and_saveexec_b64 s[2:3], s[4:5]
	s_cbranch_execz .LBB0_704
	v_lshl_add_u64 v[2:3], v[88:89], 2, s[0:1]
	s_waitcnt lgkmcnt(0)
	v_add_f32_e32 v0, v0, v1
	global_atomic_add_f32 v[2:3], v0, off

.LBB0_956:
	s_add_u32 s6, s96, 0x3500000
	s_addc_u32 s7, s97, 0
	s_add_u32 s10, s96, 0x30000
	s_addc_u32 s11, s97, 0
	s_lshl_b32 s50, s40, 8
	s_cmp_eq_u32 s78, 0
	s_cselect_b64 s[8:9], -1, 0
	s_cmp_lg_u32 s78, 0
	s_cbranch_scc1 .LBB0_974
	v_lshl_or_b32 v128, v199, 3, s33
	v_add_u32_e32 v166, s50, v132
	v_or_b32_e32 v128, s19, v128
	v_mov_b32_e32 v165, 0
	v_lshlrev_b32_e32 v164, 1, v128
	v_ashrrev_i32_e32 v167, 31, v166
	v_lshl_add_u64 v[168:169], s[6:7], 0, v[164:165]
	v_lshlrev_b64 v[208:209], 11, v[166:167]
	v_lshl_add_u64 v[128:129], v[168:169], 0, v[208:209]
	global_load_dwordx4 v[200:203], v[128:129], off
	global_load_dwordx4 v[204:207], v[128:129], off offset:256
	v_or_b32_e32 v178, 16, v166
	v_or_b32_e32 v174, 32, v166
	v_or_b32_e32 v170, 48, v166
	v_ashrrev_i32_e32 v179, 31, v178
	v_ashrrev_i32_e32 v175, 31, v174
	v_ashrrev_i32_e32 v171, 31, v170
	v_lshlrev_b64 v[180:181], 11, v[178:179]
	v_lshlrev_b64 v[176:177], 11, v[174:175]
	v_lshlrev_b64 v[172:173], 11, v[170:171]
	v_lshl_add_u64 v[128:129], v[168:169], 0, v[180:181]
	v_lshl_add_u64 v[130:131], v[168:169], 0, v[176:177]
	v_lshl_add_u64 v[210:211], v[168:169], 0, v[172:173]
	global_load_dwordx4 v[148:151], v[128:129], off
	global_load_dwordx4 v[144:147], v[128:129], off offset:256
	global_load_dwordx4 v[140:143], v[130:131], off
	global_load_dwordx4 v[136:139], v[130:131], off offset:256
	global_load_dwordx4 v[132:135], v[210:211], off
	s_nop 0
	global_load_dwordx4 v[128:131], v[210:211], off offset:256
	s_add_u32 s98, s6, 0x40000
	s_addc_u32 s99, s7, 0
	v_lshl_add_u32 v252, v166, 11, v164
	global_load_dwordx4 v[216:219], v252, s[98:99]
	global_load_dwordx4 v[220:223], v252, s[98:99] offset:256
	v_add_u32_e32 v252, 0x8000, v252
	global_load_dwordx4 v[228:231], v252, s[98:99]
	global_load_dwordx4 v[232:235], v252, s[98:99] offset:256
	v_add_u32_e32 v252, 0x8000, v252
	global_load_dwordx4 v[236:239], v252, s[98:99]
	global_load_dwordx4 v[240:243], v252, s[98:99] offset:256
	v_add_u32_e32 v252, 0x8000, v252
	global_load_dwordx4 v[244:247], v252, s[98:99]
	global_load_dwordx4 v[248:251], v252, s[98:99] offset:256
	v_cmp_eq_u32_e32 vcc, 0, v199
	v_xor_b32_e32 v199, 16, v195
	v_cmp_lt_i32_e64 s[0:1], v199, v198
	s_waitcnt vmcnt(8)
	v_lshlrev_b32_e32 v198, 16, v200
	v_cndmask_b32_e64 v195, v195, v199, s[0:1]
	v_and_b32_e32 v199, 0xffff0000, v200
	v_lshlrev_b32_e32 v200, 16, v201
	v_and_b32_e32 v201, 0xffff0000, v201
	v_lshlrev_b32_e32 v212, 16, v204
	v_and_b32_e32 v213, 0xffff0000, v204
	v_lshlrev_b32_e32 v204, 16, v205
	v_and_b32_e32 v205, 0xffff0000, v205
	v_lshlrev_b32_e32 v210, 16, v202
	v_and_b32_e32 v211, 0xffff0000, v202
	v_lshlrev_b32_e32 v202, 16, v203
	v_and_b32_e32 v203, 0xffff0000, v203
	v_lshlrev_b32_e32 v214, 16, v206
	v_and_b32_e32 v215, 0xffff0000, v206
	v_pk_add_f32 v[126:127], v[126:127], v[200:201]
	v_pk_add_f32 v[124:125], v[124:125], v[198:199]
	v_pk_add_f32 v[118:119], v[118:119], v[204:205]
	v_pk_add_f32 v[116:117], v[116:117], v[212:213]
	v_lshlrev_b32_e32 v206, 16, v207
	v_and_b32_e32 v207, 0xffff0000, v207
	v_pk_add_f32 v[122:123], v[122:123], v[202:203]
	v_pk_add_f32 v[120:121], v[120:121], v[210:211]
	v_pk_add_f32 v[200:201], v[112:113], v[214:215]
	v_cvt_pk_bf16_f32 v112, v124, v125
	v_cvt_pk_bf16_f32 v113, v126, v127
	v_mul_f32_e32 v125, v125, v125
	v_mul_f32_e32 v127, v127, v127
	v_mul_f32_e32 v202, v117, v117
	v_mul_f32_e32 v203, v119, v119
	v_pk_add_f32 v[198:199], v[114:115], v[206:207]
	v_cvt_pk_bf16_f32 v114, v120, v121
	v_cvt_pk_bf16_f32 v115, v122, v123
	v_mul_f32_e32 v121, v121, v121
	v_mul_f32_e32 v123, v123, v123
	v_mul_f32_e32 v204, v201, v201
	v_fmac_f32_e32 v125, v124, v124
	v_fmac_f32_e32 v127, v126, v126
	v_fmac_f32_e32 v202, v116, v116
	v_fmac_f32_e32 v203, v118, v118
	v_mul_f32_e32 v205, v199, v199
	v_fmac_f32_e32 v121, v120, v120
	v_fmac_f32_e32 v123, v122, v122
	v_fmac_f32_e32 v204, v200, v200
	v_add_f32_e32 v120, v125, v127
	v_add_f32_e32 v122, v202, v203
	v_fmac_f32_e32 v205, v198, v198
	v_add_f32_e32 v120, v121, v120
	v_add_f32_e32 v121, v204, v122
	v_add_f32_e32 v120, v123, v120
	v_add_f32_e32 v121, v205, v121
	v_lshlrev_b32_e32 v195, 2, v195
	v_add_f32_e32 v122, v120, v121
	ds_bpermute_b32 v123, v195, v122
	v_lshl_add_u64 v[120:121], s[6:7], 0, v[208:209]
	v_lshl_add_u64 v[120:121], v[120:121], 0, v[164:165]
	global_store_dwordx4 v[120:121], v[112:115], off
	s_waitcnt lgkmcnt(0)
	s_nop 0
	v_add_f32_e32 v112, v122, v123
	ds_bpermute_b32 v113, v194, v112
	v_cvt_pk_bf16_f32 v114, v116, v117
	v_cvt_pk_bf16_f32 v115, v118, v119
	v_cvt_pk_bf16_f32 v116, v200, v201
	v_cvt_pk_bf16_f32 v117, v198, v199
	global_store_dwordx4 v[120:121], v[114:117], off offset:256
	s_and_saveexec_b64 s[0:1], vcc
	s_cbranch_execz .LBB0_959
	v_lshl_add_u64 v[114:115], v[166:167], 2, s[10:11]
	s_waitcnt lgkmcnt(0)
	v_add_f32_e32 v112, v112, v113
	global_atomic_add_f32 v[114:115], v112, off

.LBB0_965:
	s_or_b64 exec, exec, s[0:1]
	v_add_u32_e32 v100, 0x80, v166
	v_ashrrev_i32_e32 v101, 31, v100
	v_lshlrev_b64 v[110:111], 11, v[100:101]
	s_waitcnt lgkmcnt(0)
	v_lshl_add_u64 v[64:65], v[168:169], 0, v[110:111]
	v_add_u32_e32 v96, 0x90, v166
	v_add_u32_e32 v92, 0xa0, v166
	v_add_u32_e32 v88, 0xb0, v166
	v_ashrrev_i32_e32 v97, 31, v96
	v_ashrrev_i32_e32 v93, 31, v92
	v_ashrrev_i32_e32 v89, 31, v88
	v_lshlrev_b64 v[98:99], 11, v[96:97]
	v_lshlrev_b64 v[94:95], 11, v[92:93]
	v_lshlrev_b64 v[90:91], 11, v[88:89]
	v_lshl_add_u64 v[64:65], v[168:169], 0, v[98:99]
	v_lshl_add_u64 v[66:67], v[168:169], 0, v[94:95]
	v_lshl_add_u64 v[112:113], v[168:169], 0, v[90:91]
	s_nop 0
	v_lshl_add_u64 v[110:111], s[6:7], 0, v[110:111]
	v_mov_b32_e32 v165, 0
	s_waitcnt vmcnt(8)
	v_lshlrev_b32_e32 v112, 16, v216
	v_and_b32_e32 v113, 0xffff0000, v216
	v_lshlrev_b32_e32 v102, 16, v217
	v_and_b32_e32 v103, 0xffff0000, v217
	v_lshlrev_b32_e32 v116, 16, v220
	v_and_b32_e32 v117, 0xffff0000, v220
	v_lshlrev_b32_e32 v106, 16, v221
	v_and_b32_e32 v107, 0xffff0000, v221
	v_lshlrev_b32_e32 v114, 16, v218
	v_and_b32_e32 v115, 0xffff0000, v218
	v_lshlrev_b32_e32 v104, 16, v219
	v_and_b32_e32 v105, 0xffff0000, v219
	v_lshlrev_b32_e32 v118, 16, v222
	v_and_b32_e32 v119, 0xffff0000, v222
	v_pk_add_f32 v[62:63], v[62:63], v[102:103]
	v_pk_add_f32 v[60:61], v[60:61], v[112:113]
	v_pk_add_f32 v[54:55], v[54:55], v[106:107]
	v_pk_add_f32 v[52:53], v[52:53], v[116:117]
	v_lshlrev_b32_e32 v108, 16, v223
	v_and_b32_e32 v109, 0xffff0000, v223
	v_pk_add_f32 v[58:59], v[58:59], v[104:105]
	v_pk_add_f32 v[56:57], v[56:57], v[114:115]
	v_pk_add_f32 v[104:105], v[48:49], v[118:119]
	v_cvt_pk_bf16_f32 v48, v60, v61
	v_cvt_pk_bf16_f32 v49, v62, v63
	v_mul_f32_e32 v61, v61, v61
	v_mul_f32_e32 v63, v63, v63
	v_mul_f32_e32 v106, v53, v53
	v_mul_f32_e32 v107, v55, v55
	v_pk_add_f32 v[102:103], v[50:51], v[108:109]
	v_cvt_pk_bf16_f32 v50, v56, v57
	v_cvt_pk_bf16_f32 v51, v58, v59
	v_mul_f32_e32 v57, v57, v57
	v_mul_f32_e32 v59, v59, v59
	v_mul_f32_e32 v108, v105, v105
	v_fmac_f32_e32 v61, v60, v60
	v_fmac_f32_e32 v63, v62, v62
	v_fmac_f32_e32 v106, v52, v52
	v_fmac_f32_e32 v107, v54, v54
	v_mul_f32_e32 v109, v103, v103
	v_fmac_f32_e32 v57, v56, v56
	v_fmac_f32_e32 v59, v58, v58
	v_fmac_f32_e32 v108, v104, v104
	v_add_f32_e32 v56, v61, v63
	v_add_f32_e32 v58, v106, v107
	v_fmac_f32_e32 v109, v102, v102
	v_add_f32_e32 v56, v57, v56
	v_add_f32_e32 v57, v108, v58
	v_add_f32_e32 v56, v59, v56
	v_add_f32_e32 v57, v109, v57
	v_add_f32_e32 v58, v56, v57
	ds_bpermute_b32 v59, v195, v58
	v_lshl_add_u64 v[56:57], v[110:111], 0, v[164:165]
	global_store_dwordx4 v[56:57], v[48:51], off
	s_waitcnt lgkmcnt(0)
	s_nop 0
	v_add_f32_e32 v48, v58, v59
	ds_bpermute_b32 v49, v194, v48
	v_cvt_pk_bf16_f32 v50, v52, v53
	v_cvt_pk_bf16_f32 v51, v54, v55
	v_cvt_pk_bf16_f32 v52, v104, v105
	v_cvt_pk_bf16_f32 v53, v102, v103
	global_store_dwordx4 v[56:57], v[50:53], off offset:256
	s_and_saveexec_b64 s[0:1], vcc
	s_cbranch_execz .LBB0_967
	v_lshl_add_u64 v[50:51], v[100:101], 2, s[10:11]
	s_waitcnt lgkmcnt(0)
	v_add_f32_e32 v48, v48, v49
	global_atomic_add_f32 v[50:51], v48, off
.LBB0_967:
	s_or_b64 exec, exec, s[0:1]
	v_lshlrev_b32_e32 v48, 16, v228
	s_waitcnt lgkmcnt(0)
	v_and_b32_e32 v49, 0xffff0000, v228
	v_lshlrev_b32_e32 v50, 16, v229
	v_and_b32_e32 v51, 0xffff0000, v229
	v_lshlrev_b32_e32 v52, 16, v230
	v_and_b32_e32 v53, 0xffff0000, v230
	v_pk_add_f32 v[44:45], v[44:45], v[48:49]
	v_pk_add_f32 v[46:47], v[46:47], v[50:51]
	v_pk_add_f32 v[50:51], v[40:41], v[52:53]
	v_cvt_pk_bf16_f32 v40, v44, v45
	v_mul_f32_e32 v45, v45, v45
	v_fmac_f32_e32 v45, v44, v44
	v_mul_f32_e32 v44, v47, v47
	v_lshlrev_b32_e32 v56, 16, v232
	v_and_b32_e32 v57, 0xffff0000, v232
	v_lshlrev_b32_e32 v58, 16, v233
	v_and_b32_e32 v59, 0xffff0000, v233
	v_fmac_f32_e32 v44, v46, v46
	v_lshlrev_b32_e32 v54, 16, v231
	v_and_b32_e32 v55, 0xffff0000, v231
	v_lshlrev_b32_e32 v60, 16, v234
	v_and_b32_e32 v61, 0xffff0000, v234
	v_add_f32_e32 v44, v45, v44
	v_mul_f32_e32 v45, v51, v51
	v_pk_add_f32 v[38:39], v[38:39], v[58:59]
	v_pk_add_f32 v[36:37], v[36:37], v[56:57]
	v_pk_add_f32 v[48:49], v[42:43], v[54:55]
	v_cvt_pk_bf16_f32 v41, v46, v47
	v_fmac_f32_e32 v45, v50, v50
	v_pk_add_f32 v[46:47], v[32:33], v[60:61]
	v_mul_f32_e32 v32, v37, v37
	v_mul_f32_e32 v33, v39, v39
	v_add_f32_e32 v44, v45, v44
	v_mul_f32_e32 v45, v49, v49
	v_fmac_f32_e32 v32, v36, v36
	v_fmac_f32_e32 v33, v38, v38
	v_lshlrev_b32_e32 v62, 16, v235
	v_and_b32_e32 v63, 0xffff0000, v235
	v_fmac_f32_e32 v45, v48, v48
	v_add_f32_e32 v32, v32, v33
	v_mul_f32_e32 v33, v47, v47
	v_cvt_pk_bf16_f32 v43, v48, v49
	v_add_f32_e32 v48, v45, v44
	v_pk_add_f32 v[44:45], v[34:35], v[62:63]
	v_fmac_f32_e32 v33, v46, v46
	v_add_f32_e32 v32, v33, v32
	v_mul_f32_e32 v33, v45, v45
	v_fmac_f32_e32 v33, v44, v44
	v_add_f32_e32 v32, v33, v32
	v_add_f32_e32 v35, v48, v32
	v_cvt_pk_bf16_f32 v42, v50, v51
	ds_bpermute_b32 v50, v195, v35
	v_lshl_add_u64 v[32:33], s[6:7], 0, v[98:99]
	v_lshl_add_u64 v[48:49], v[32:33], 0, v[164:165]
	v_cvt_pk_bf16_f32 v34, v36, v37
	v_cvt_pk_bf16_f32 v36, v46, v47
	s_waitcnt lgkmcnt(0)
	v_add_f32_e32 v32, v35, v50
	ds_bpermute_b32 v33, v194, v32
	v_cvt_pk_bf16_f32 v35, v38, v39
	v_cvt_pk_bf16_f32 v37, v44, v45
	global_store_dwordx4 v[48:49], v[40:43], off
	global_store_dwordx4 v[48:49], v[34:37], off offset:256
	s_and_saveexec_b64 s[0:1], vcc
	s_cbranch_execz .LBB0_969
	v_lshl_add_u64 v[34:35], v[96:97], 2, s[10:11]
	s_waitcnt lgkmcnt(0)
	v_add_f32_e32 v32, v32, v33
	global_atomic_add_f32 v[34:35], v32, off
.LBB0_969:
	s_or_b64 exec, exec, s[0:1]
	v_lshlrev_b32_e32 v32, 16, v236
	s_waitcnt lgkmcnt(0)
	v_and_b32_e32 v33, 0xffff0000, v236
	v_lshlrev_b32_e32 v34, 16, v237
	v_and_b32_e32 v35, 0xffff0000, v237
	v_lshlrev_b32_e32 v36, 16, v238
	v_and_b32_e32 v37, 0xffff0000, v238
	v_pk_add_f32 v[28:29], v[28:29], v[32:33]
	v_pk_add_f32 v[30:31], v[30:31], v[34:35]
	v_pk_add_f32 v[34:35], v[24:25], v[36:37]
	v_cvt_pk_bf16_f32 v24, v28, v29
	v_mul_f32_e32 v29, v29, v29
	v_fmac_f32_e32 v29, v28, v28
	v_mul_f32_e32 v28, v31, v31
	v_lshlrev_b32_e32 v40, 16, v240
	v_and_b32_e32 v41, 0xffff0000, v240
	v_lshlrev_b32_e32 v42, 16, v241
	v_and_b32_e32 v43, 0xffff0000, v241
	v_fmac_f32_e32 v28, v30, v30
	v_lshlrev_b32_e32 v38, 16, v239
	v_and_b32_e32 v39, 0xffff0000, v239
	v_lshlrev_b32_e32 v44, 16, v242
	v_and_b32_e32 v45, 0xffff0000, v242
	v_add_f32_e32 v28, v29, v28
	v_mul_f32_e32 v29, v35, v35
	v_pk_add_f32 v[22:23], v[22:23], v[42:43]
	v_pk_add_f32 v[20:21], v[20:21], v[40:41]
	v_pk_add_f32 v[32:33], v[26:27], v[38:39]
	v_cvt_pk_bf16_f32 v25, v30, v31
	v_fmac_f32_e32 v29, v34, v34
	v_pk_add_f32 v[30:31], v[16:17], v[44:45]
	v_mul_f32_e32 v16, v21, v21
	v_mul_f32_e32 v17, v23, v23
	v_add_f32_e32 v28, v29, v28
	v_mul_f32_e32 v29, v33, v33
	v_fmac_f32_e32 v16, v20, v20
	v_fmac_f32_e32 v17, v22, v22
	v_lshlrev_b32_e32 v46, 16, v243
	v_and_b32_e32 v47, 0xffff0000, v243
	v_fmac_f32_e32 v29, v32, v32
	v_add_f32_e32 v16, v16, v17
	v_mul_f32_e32 v17, v31, v31
	v_cvt_pk_bf16_f32 v27, v32, v33
	v_add_f32_e32 v32, v29, v28
	v_pk_add_f32 v[28:29], v[18:19], v[46:47]
	v_fmac_f32_e32 v17, v30, v30
	v_add_f32_e32 v16, v17, v16
	v_mul_f32_e32 v17, v29, v29
	v_fmac_f32_e32 v17, v28, v28
	v_add_f32_e32 v16, v17, v16
	v_add_f32_e32 v16, v32, v16
	ds_bpermute_b32 v17, v195, v16
	v_lshl_add_u64 v[36:37], s[6:7], 0, v[94:95]
	v_mov_b32_e32 v165, 0
	v_cvt_pk_bf16_f32 v26, v34, v35
	v_lshl_add_u64 v[32:33], v[36:37], 0, v[164:165]
	s_waitcnt lgkmcnt(0)
	v_add_f32_e32 v16, v16, v17
	ds_bpermute_b32 v17, v194, v16
	v_cvt_pk_bf16_f32 v18, v20, v21
	v_cvt_pk_bf16_f32 v19, v22, v23
	v_cvt_pk_bf16_f32 v20, v30, v31
	v_cvt_pk_bf16_f32 v21, v28, v29
	global_store_dwordx4 v[32:33], v[24:27], off
	global_store_dwordx4 v[32:33], v[18:21], off offset:256
	s_and_saveexec_b64 s[0:1], vcc
	s_cbranch_execz .LBB0_971
	v_lshl_add_u64 v[18:19], v[92:93], 2, s[10:11]
	s_waitcnt lgkmcnt(0)
	v_add_f32_e32 v16, v16, v17
	global_atomic_add_f32 v[18:19], v16, off
.LBB0_971:
	s_or_b64 exec, exec, s[0:1]
	v_lshlrev_b32_e32 v16, 16, v244
	s_waitcnt lgkmcnt(0)
	v_and_b32_e32 v17, 0xffff0000, v244
	v_lshlrev_b32_e32 v18, 16, v245
	v_and_b32_e32 v19, 0xffff0000, v245
	v_lshlrev_b32_e32 v20, 16, v246
	v_and_b32_e32 v21, 0xffff0000, v246
	v_pk_add_f32 v[12:13], v[12:13], v[16:17]
	v_pk_add_f32 v[14:15], v[14:15], v[18:19]
	v_pk_add_f32 v[18:19], v[8:9], v[20:21]
	v_cvt_pk_bf16_f32 v8, v12, v13
	v_mul_f32_e32 v13, v13, v13
	v_fmac_f32_e32 v13, v12, v12
	v_mul_f32_e32 v12, v15, v15
	v_lshlrev_b32_e32 v24, 16, v248
	v_and_b32_e32 v25, 0xffff0000, v248
	v_lshlrev_b32_e32 v26, 16, v249
	v_and_b32_e32 v27, 0xffff0000, v249
	v_fmac_f32_e32 v12, v14, v14
	v_lshlrev_b32_e32 v22, 16, v247
	v_and_b32_e32 v23, 0xffff0000, v247
	v_lshlrev_b32_e32 v28, 16, v250
	v_and_b32_e32 v29, 0xffff0000, v250
	v_add_f32_e32 v12, v13, v12
	v_mul_f32_e32 v13, v19, v19
	v_pk_add_f32 v[6:7], v[6:7], v[26:27]
	v_pk_add_f32 v[4:5], v[4:5], v[24:25]
	v_pk_add_f32 v[16:17], v[10:11], v[22:23]
	v_cvt_pk_bf16_f32 v9, v14, v15
	v_fmac_f32_e32 v13, v18, v18
	v_pk_add_f32 v[14:15], v[0:1], v[28:29]
	v_mul_f32_e32 v0, v5, v5
	v_mul_f32_e32 v1, v7, v7
	v_add_f32_e32 v12, v13, v12
	v_mul_f32_e32 v13, v17, v17
	v_fmac_f32_e32 v0, v4, v4
	v_fmac_f32_e32 v1, v6, v6
	v_lshlrev_b32_e32 v30, 16, v251
	v_and_b32_e32 v31, 0xffff0000, v251
	v_fmac_f32_e32 v13, v16, v16
	v_add_f32_e32 v0, v0, v1
	v_mul_f32_e32 v1, v15, v15
	v_cvt_pk_bf16_f32 v11, v16, v17
	v_add_f32_e32 v16, v13, v12
	v_pk_add_f32 v[12:13], v[2:3], v[30:31]
	v_fmac_f32_e32 v1, v14, v14
	v_add_f32_e32 v0, v1, v0
	v_mul_f32_e32 v1, v13, v13
	v_fmac_f32_e32 v1, v12, v12
	v_add_f32_e32 v0, v1, v0
	v_add_f32_e32 v3, v16, v0
	v_cvt_pk_bf16_f32 v10, v18, v19
	ds_bpermute_b32 v18, v195, v3
	v_lshl_add_u64 v[0:1], s[6:7], 0, v[90:91]
	v_lshl_add_u64 v[16:17], v[0:1], 0, v[164:165]
	v_cvt_pk_bf16_f32 v2, v4, v5
	v_cvt_pk_bf16_f32 v4, v14, v15
	s_waitcnt lgkmcnt(0)
	v_add_f32_e32 v0, v3, v18
	ds_bpermute_b32 v1, v194, v0
	v_cvt_pk_bf16_f32 v3, v6, v7
	v_cvt_pk_bf16_f32 v5, v12, v13
	global_store_dwordx4 v[16:17], v[8:11], off
	global_store_dwordx4 v[16:17], v[2:5], off offset:256
	s_and_saveexec_b64 s[0:1], vcc
	s_cbranch_execz .LBB0_973
	v_lshl_add_u64 v[2:3], v[88:89], 2, s[10:11]
	s_waitcnt lgkmcnt(0)
	v_add_f32_e32 v0, v0, v1
	global_atomic_add_f32 v[2:3], v0, off

.LBB0_1020:
	s_andn2_b64 vcc, exec, s[8:9]
	s_cbranch_vccnz .LBB0_1022
	s_or_b32 s0, s21, s33
	v_or_b32_e32 v204, s0, v182
	v_add_u32_e32 v132, s50, v141
	v_lshlrev_b32_e32 v128, 1, v204
	v_mov_b32_e32 v129, 0
	v_ashrrev_i32_e32 v133, 31, v132
	v_lshl_add_u64 v[130:131], s[6:7], 0, v[128:129]
	v_lshlrev_b64 v[134:135], 11, v[132:133]
	v_lshl_add_u64 v[134:135], v[130:131], 0, v[134:135]
	v_or_b32_e32 v168, 16, v132
	global_load_dwordx4 v[136:139], v[134:135], off
	global_load_dwordx4 v[140:143], v[134:135], off offset:256
	v_ashrrev_i32_e32 v169, 31, v168
	v_lshlrev_b64 v[134:135], 11, v[168:169]
	v_or_b32_e32 v170, 32, v132
	v_lshl_add_u64 v[134:135], v[130:131], 0, v[134:135]
	v_ashrrev_i32_e32 v171, 31, v170
	global_load_dwordx4 v[144:147], v[134:135], off
	global_load_dwordx4 v[148:151], v[134:135], off offset:256
	v_lshlrev_b64 v[134:135], 11, v[170:171]
	v_lshl_add_u64 v[134:135], v[130:131], 0, v[134:135]
	global_load_dwordx4 v[152:155], v[134:135], off
	global_load_dwordx4 v[156:159], v[134:135], off offset:256
	v_or_b32_e32 v134, 48, v132
	v_ashrrev_i32_e32 v135, 31, v134
	v_lshlrev_b64 v[160:161], 11, v[134:135]
	v_lshl_add_u64 v[164:165], v[130:131], 0, v[160:161]
	global_load_dwordx4 v[160:163], v[164:165], off
	s_nop 0
	global_load_dwordx4 v[164:167], v[164:165], off offset:256
	s_add_u32 s98, s6, 0x40000
	s_addc_u32 s99, s7, 0
	v_lshl_add_u32 v252, v132, 11, v128
	global_load_dwordx4 v[208:211], v252, s[98:99]
	global_load_dwordx4 v[212:215], v252, s[98:99] offset:256
	v_add_u32_e32 v252, 0x8000, v252
	global_load_dwordx4 v[216:219], v252, s[98:99]
	global_load_dwordx4 v[220:223], v252, s[98:99] offset:256
	v_add_u32_e32 v252, 0x8000, v252
	global_load_dwordx4 v[224:227], v252, s[98:99]
	global_load_dwordx4 v[228:231], v252, s[98:99] offset:256
	v_add_u32_e32 v252, 0x8000, v252
	global_load_dwordx4 v[232:235], v252, s[98:99]
	global_load_dwordx4 v[236:239], v252, s[98:99] offset:256
	v_readlane_b32 s0, v254, 0
	v_readlane_b32 s2, v254, 2
	v_readlane_b32 s3, v254, 3
	v_lshlrev_b32_e32 v128, 2, v204
	v_readlane_b32 s1, v254, 1
	s_waitcnt vmcnt(8)
	v_lshlrev_b32_e32 v172, 16, v136
	v_and_b32_e32 v173, 0xffff0000, v136
	v_lshlrev_b32_e32 v136, 16, v137
	v_and_b32_e32 v137, 0xffff0000, v137
	v_pk_add_f32 v[126:127], v[126:127], v[136:137]
	v_lshlrev_b64 v[136:137], 12, v[132:133]
	v_lshlrev_b32_e32 v176, 16, v140
	v_and_b32_e32 v177, 0xffff0000, v140
	v_lshlrev_b32_e32 v140, 16, v141
	v_and_b32_e32 v141, 0xffff0000, v141
	v_lshlrev_b32_e32 v178, 16, v142
	v_and_b32_e32 v179, 0xffff0000, v142
	v_lshl_add_u64 v[136:137], s[2:3], 0, v[136:137]
	v_lshlrev_b32_e32 v174, 16, v138
	v_and_b32_e32 v175, 0xffff0000, v138
	v_lshlrev_b32_e32 v138, 16, v139
	v_and_b32_e32 v139, 0xffff0000, v139
	v_lshlrev_b32_e32 v142, 16, v143
	v_and_b32_e32 v143, 0xffff0000, v143
	v_lshlrev_b32_e32 v180, 16, v144
	v_and_b32_e32 v181, 0xffff0000, v144
	v_pk_add_f32 v[124:125], v[124:125], v[172:173]
	v_lshl_add_u64 v[136:137], v[136:137], 0, v[128:129]
	v_pk_add_f32 v[118:119], v[118:119], v[140:141]
	v_pk_add_f32 v[116:117], v[116:117], v[176:177]
	v_pk_add_f32 v[108:109], v[108:109], v[178:179]
	v_pk_add_f32 v[122:123], v[122:123], v[138:139]
	v_pk_add_f32 v[120:121], v[120:121], v[174:175]
	global_store_dwordx4 v[136:137], v[124:127], off
	global_store_dwordx4 v[136:137], v[120:123], off offset:16
	v_pk_add_f32 v[110:111], v[110:111], v[142:143]
	global_store_dwordx4 v[136:137], v[116:119], off offset:512
	global_store_dwordx4 v[136:137], v[108:111], off offset:528
	v_lshlrev_b32_e32 v144, 16, v145
	v_and_b32_e32 v145, 0xffff0000, v145
	v_pk_add_f32 v[108:109], v[112:113], v[180:181]
	v_lshlrev_b64 v[112:113], 12, v[168:169]
	v_lshlrev_b32_e32 v184, 16, v148
	v_and_b32_e32 v185, 0xffff0000, v148
	v_lshlrev_b32_e32 v148, 16, v149
	v_and_b32_e32 v149, 0xffff0000, v149
	v_lshlrev_b32_e32 v186, 16, v150
	v_and_b32_e32 v187, 0xffff0000, v150
	v_lshl_add_u64 v[112:113], s[2:3], 0, v[112:113]
	v_lshlrev_b32_e32 v182, 16, v146
	v_and_b32_e32 v183, 0xffff0000, v146
	v_lshlrev_b32_e32 v146, 16, v147
	v_and_b32_e32 v147, 0xffff0000, v147
	v_lshlrev_b32_e32 v150, 16, v151
	v_and_b32_e32 v151, 0xffff0000, v151
	v_lshlrev_b32_e32 v188, 16, v152
	v_and_b32_e32 v189, 0xffff0000, v152
	v_pk_add_f32 v[110:111], v[114:115], v[144:145]
	v_lshl_add_u64 v[112:113], v[112:113], 0, v[128:129]
	v_pk_add_f32 v[102:103], v[102:103], v[148:149]
	v_pk_add_f32 v[100:101], v[100:101], v[184:185]
	v_pk_add_f32 v[92:93], v[92:93], v[186:187]
	v_pk_add_f32 v[106:107], v[106:107], v[146:147]
	v_pk_add_f32 v[104:105], v[104:105], v[182:183]
	global_store_dwordx4 v[112:113], v[108:111], off
	global_store_dwordx4 v[112:113], v[104:107], off offset:16
	v_pk_add_f32 v[94:95], v[94:95], v[150:151]
	global_store_dwordx4 v[112:113], v[100:103], off offset:512
	global_store_dwordx4 v[112:113], v[92:95], off offset:528
	v_lshlrev_b32_e32 v152, 16, v153
	v_and_b32_e32 v153, 0xffff0000, v153
	v_pk_add_f32 v[92:93], v[96:97], v[188:189]
	v_lshlrev_b64 v[96:97], 12, v[170:171]
	v_lshlrev_b32_e32 v192, 16, v156
	v_and_b32_e32 v193, 0xffff0000, v156
	v_lshlrev_b32_e32 v156, 16, v157
	v_and_b32_e32 v157, 0xffff0000, v157
	v_lshlrev_b32_e32 v194, 16, v158
	v_and_b32_e32 v195, 0xffff0000, v158
	v_lshl_add_u64 v[96:97], s[2:3], 0, v[96:97]
	v_lshlrev_b32_e32 v190, 16, v154
	v_and_b32_e32 v191, 0xffff0000, v154
	v_lshlrev_b32_e32 v154, 16, v155
	v_and_b32_e32 v155, 0xffff0000, v155
	v_lshlrev_b32_e32 v158, 16, v159
	v_and_b32_e32 v159, 0xffff0000, v159
	v_lshlrev_b32_e32 v196, 16, v160
	v_and_b32_e32 v197, 0xffff0000, v160
	v_pk_add_f32 v[94:95], v[98:99], v[152:153]
	v_lshl_add_u64 v[96:97], v[96:97], 0, v[128:129]
	v_pk_add_f32 v[86:87], v[86:87], v[156:157]
	v_pk_add_f32 v[84:85], v[84:85], v[192:193]
	v_pk_add_f32 v[76:77], v[76:77], v[194:195]
	v_pk_add_f32 v[90:91], v[90:91], v[154:155]
	v_pk_add_f32 v[88:89], v[88:89], v[190:191]
	global_store_dwordx4 v[96:97], v[92:95], off
	global_store_dwordx4 v[96:97], v[88:91], off offset:16
	v_pk_add_f32 v[78:79], v[78:79], v[158:159]
	global_store_dwordx4 v[96:97], v[84:87], off offset:512
	global_store_dwordx4 v[96:97], v[76:79], off offset:528
	v_lshlrev_b32_e32 v160, 16, v161
	v_and_b32_e32 v161, 0xffff0000, v161
	v_pk_add_f32 v[76:77], v[80:81], v[196:197]
	v_lshlrev_b64 v[80:81], 12, v[134:135]
	v_lshlrev_b32_e32 v200, 16, v164
	v_and_b32_e32 v201, 0xffff0000, v164
	v_lshlrev_b32_e32 v164, 16, v165
	v_and_b32_e32 v165, 0xffff0000, v165
	v_lshlrev_b32_e32 v202, 16, v166
	v_and_b32_e32 v203, 0xffff0000, v166
	v_lshl_add_u64 v[80:81], s[2:3], 0, v[80:81]
	v_add_u32_e32 v98, 0x80, v132
	v_lshlrev_b32_e32 v198, 16, v162
	v_and_b32_e32 v199, 0xffff0000, v162
	v_lshlrev_b32_e32 v162, 16, v163
	v_and_b32_e32 v163, 0xffff0000, v163
	v_lshlrev_b32_e32 v166, 16, v167
	v_and_b32_e32 v167, 0xffff0000, v167
	v_pk_add_f32 v[78:79], v[82:83], v[160:161]
	v_lshl_add_u64 v[80:81], v[80:81], 0, v[128:129]
	v_pk_add_f32 v[70:71], v[70:71], v[164:165]
	v_pk_add_f32 v[68:69], v[68:69], v[200:201]
	v_pk_add_f32 v[64:65], v[64:65], v[202:203]
	v_ashrrev_i32_e32 v99, 31, v98
	v_pk_add_f32 v[74:75], v[74:75], v[162:163]
	v_pk_add_f32 v[72:73], v[72:73], v[198:199]
	global_store_dwordx4 v[80:81], v[76:79], off
	global_store_dwordx4 v[80:81], v[72:75], off offset:16
	v_pk_add_f32 v[66:67], v[66:67], v[166:167]
	global_store_dwordx4 v[80:81], v[68:71], off offset:512
	global_store_dwordx4 v[80:81], v[64:67], off offset:528
	v_add_u32_e32 v100, 0x90, v132
	v_ashrrev_i32_e32 v101, 31, v100
	v_lshlrev_b64 v[64:65], 11, v[98:99]
	v_lshl_add_u64 v[64:65], v[130:131], 0, v[64:65]
	v_lshlrev_b64 v[64:65], 11, v[100:101]
	v_add_u32_e32 v102, 0xa0, v132
	v_lshl_add_u64 v[64:65], v[130:131], 0, v[64:65]
	v_ashrrev_i32_e32 v103, 31, v102
	v_lshlrev_b64 v[64:65], 11, v[102:103]
	v_lshl_add_u64 v[64:65], v[130:131], 0, v[64:65]
	v_add_u32_e32 v64, 0xb0, v132
	v_ashrrev_i32_e32 v65, 31, v64
	v_lshlrev_b64 v[90:91], 11, v[64:65]
	v_lshl_add_u64 v[104:105], v[130:131], 0, v[90:91]
	s_waitcnt vmcnt(8)
	v_lshlrev_b32_e32 v104, 16, v208
	v_and_b32_e32 v105, 0xffff0000, v208
	v_lshlrev_b32_e32 v66, 16, v209
	v_and_b32_e32 v67, 0xffff0000, v209
	v_pk_add_f32 v[62:63], v[62:63], v[66:67]
	v_lshlrev_b64 v[66:67], 12, v[98:99]
	v_lshlrev_b32_e32 v108, 16, v212
	v_and_b32_e32 v109, 0xffff0000, v212
	v_lshlrev_b32_e32 v70, 16, v213
	v_and_b32_e32 v71, 0xffff0000, v213
	v_lshlrev_b32_e32 v110, 16, v214
	v_and_b32_e32 v111, 0xffff0000, v214
	v_lshl_add_u64 v[66:67], s[2:3], 0, v[66:67]
	v_lshlrev_b32_e32 v106, 16, v210
	v_and_b32_e32 v107, 0xffff0000, v210
	v_lshlrev_b32_e32 v68, 16, v211
	v_and_b32_e32 v69, 0xffff0000, v211
	v_lshlrev_b32_e32 v72, 16, v215
	v_and_b32_e32 v73, 0xffff0000, v215
	v_lshlrev_b32_e32 v112, 16, v216
	v_and_b32_e32 v113, 0xffff0000, v216
	v_pk_add_f32 v[60:61], v[60:61], v[104:105]
	v_lshl_add_u64 v[66:67], v[66:67], 0, v[128:129]
	v_pk_add_f32 v[54:55], v[54:55], v[70:71]
	v_pk_add_f32 v[52:53], v[52:53], v[108:109]
	v_pk_add_f32 v[44:45], v[44:45], v[110:111]
	v_pk_add_f32 v[58:59], v[58:59], v[68:69]
	v_pk_add_f32 v[56:57], v[56:57], v[106:107]
	global_store_dwordx4 v[66:67], v[60:63], off
	global_store_dwordx4 v[66:67], v[56:59], off offset:16
	v_pk_add_f32 v[46:47], v[46:47], v[72:73]
	global_store_dwordx4 v[66:67], v[52:55], off offset:512
	global_store_dwordx4 v[66:67], v[44:47], off offset:528
	v_lshlrev_b32_e32 v74, 16, v217
	v_and_b32_e32 v75, 0xffff0000, v217
	v_pk_add_f32 v[44:45], v[48:49], v[112:113]
	v_lshlrev_b64 v[48:49], 12, v[100:101]
	v_lshlrev_b32_e32 v116, 16, v220
	v_and_b32_e32 v117, 0xffff0000, v220
	v_lshlrev_b32_e32 v78, 16, v221
	v_and_b32_e32 v79, 0xffff0000, v221
	v_lshlrev_b32_e32 v118, 16, v222
	v_and_b32_e32 v119, 0xffff0000, v222
	v_lshl_add_u64 v[48:49], s[2:3], 0, v[48:49]
	v_lshlrev_b32_e32 v114, 16, v218
	v_and_b32_e32 v115, 0xffff0000, v218
	v_lshlrev_b32_e32 v76, 16, v219
	v_and_b32_e32 v77, 0xffff0000, v219
	v_lshlrev_b32_e32 v80, 16, v223
	v_and_b32_e32 v81, 0xffff0000, v223
	v_lshlrev_b32_e32 v120, 16, v224
	v_and_b32_e32 v121, 0xffff0000, v224
	v_pk_add_f32 v[46:47], v[50:51], v[74:75]
	v_lshl_add_u64 v[48:49], v[48:49], 0, v[128:129]
	v_pk_add_f32 v[38:39], v[38:39], v[78:79]
	v_pk_add_f32 v[36:37], v[36:37], v[116:117]
	v_pk_add_f32 v[28:29], v[28:29], v[118:119]
	v_pk_add_f32 v[42:43], v[42:43], v[76:77]
	v_pk_add_f32 v[40:41], v[40:41], v[114:115]
	global_store_dwordx4 v[48:49], v[44:47], off
	global_store_dwordx4 v[48:49], v[40:43], off offset:16
	v_pk_add_f32 v[30:31], v[30:31], v[80:81]
	global_store_dwordx4 v[48:49], v[36:39], off offset:512
	global_store_dwordx4 v[48:49], v[28:31], off offset:528
	v_lshlrev_b32_e32 v82, 16, v225
	v_and_b32_e32 v83, 0xffff0000, v225
	v_pk_add_f32 v[28:29], v[32:33], v[120:121]
	v_lshlrev_b64 v[32:33], 12, v[102:103]
	v_lshlrev_b32_e32 v124, 16, v228
	v_and_b32_e32 v125, 0xffff0000, v228
	v_lshlrev_b32_e32 v86, 16, v229
	v_and_b32_e32 v87, 0xffff0000, v229
	v_lshlrev_b32_e32 v126, 16, v230
	v_and_b32_e32 v127, 0xffff0000, v230
	v_lshl_add_u64 v[32:33], s[2:3], 0, v[32:33]
	v_lshlrev_b32_e32 v122, 16, v226
	v_and_b32_e32 v123, 0xffff0000, v226
	v_lshlrev_b32_e32 v84, 16, v227
	v_and_b32_e32 v85, 0xffff0000, v227
	v_lshlrev_b32_e32 v88, 16, v231
	v_and_b32_e32 v89, 0xffff0000, v231
	v_lshlrev_b32_e32 v130, 16, v232
	v_and_b32_e32 v131, 0xffff0000, v232
	v_pk_add_f32 v[30:31], v[34:35], v[82:83]
	v_lshl_add_u64 v[32:33], v[32:33], 0, v[128:129]
	v_pk_add_f32 v[22:23], v[22:23], v[86:87]
	v_pk_add_f32 v[20:21], v[20:21], v[124:125]
	v_pk_add_f32 v[12:13], v[12:13], v[126:127]
	v_pk_add_f32 v[26:27], v[26:27], v[84:85]
	v_pk_add_f32 v[24:25], v[24:25], v[122:123]
	global_store_dwordx4 v[32:33], v[28:31], off
	global_store_dwordx4 v[32:33], v[24:27], off offset:16
	v_pk_add_f32 v[14:15], v[14:15], v[88:89]
	global_store_dwordx4 v[32:33], v[20:23], off offset:512
	global_store_dwordx4 v[32:33], v[12:15], off offset:528
	v_lshlrev_b32_e32 v90, 16, v233
	v_and_b32_e32 v91, 0xffff0000, v233
	v_pk_add_f32 v[12:13], v[16:17], v[130:131]
	v_lshlrev_b64 v[16:17], 12, v[64:65]
	v_lshlrev_b32_e32 v134, 16, v236
	v_and_b32_e32 v135, 0xffff0000, v236
	v_lshlrev_b32_e32 v94, 16, v237
	v_and_b32_e32 v95, 0xffff0000, v237
	v_lshl_add_u64 v[16:17], s[2:3], 0, v[16:17]
	v_lshlrev_b32_e32 v132, 16, v234
	v_and_b32_e32 v133, 0xffff0000, v234
	v_lshlrev_b32_e32 v92, 16, v235
	v_and_b32_e32 v93, 0xffff0000, v235
	v_lshlrev_b32_e32 v136, 16, v238
	v_and_b32_e32 v137, 0xffff0000, v238
	v_lshlrev_b32_e32 v96, 16, v239
	v_and_b32_e32 v97, 0xffff0000, v239
	v_pk_add_f32 v[14:15], v[18:19], v[90:91]
	v_lshl_add_u64 v[16:17], v[16:17], 0, v[128:129]
	v_pk_add_f32 v[6:7], v[6:7], v[94:95]
	v_pk_add_f32 v[4:5], v[4:5], v[134:135]
	v_pk_add_f32 v[10:11], v[10:11], v[92:93]
	v_pk_add_f32 v[8:9], v[8:9], v[132:133]
	global_store_dwordx4 v[16:17], v[12:15], off
	global_store_dwordx4 v[16:17], v[8:11], off offset:16
	v_pk_add_f32 v[2:3], v[2:3], v[96:97]
	v_pk_add_f32 v[0:1], v[0:1], v[136:137]
	global_store_dwordx4 v[16:17], v[4:7], off offset:512
	global_store_dwordx4 v[16:17], v[0:3], off offset:528
